# A+B plus 4-deep pipelined K-fragment LDS reads in MoBA QK blocks
# speedup vs baseline: 1.0016x; 1.0016x over previous
; #define LAS __attribute__((address_space(3)))
; #define MFMA32(a, b, c) __builtin_amdgcn_mfma_f32_32x32x16_bf16((a), (b), (c), 0, 0, 0)
; DI void qk_tile(f32x16& p0, f32x16& p1, LAS const unsigned char* Ks, const bf16x8 (&qf)[4], int r, int h) {
; #pragma unroll
;     for (int s = 0; s < 4; ++s) {
;         const bf16x8 k0 = *(LAS const bf16x8*)(Ks + (2 * s + h) * 1024 + r * 16);
;         const bf16x8 k1 = *(LAS const bf16x8*)(Ks + (2 * s + h) * 1024 + 512 + r * 16);
;         p0 = MFMA32(k0, qf[s], p0); p1 = MFMA32(k1, qf[s], p1);
;     }
; }
; DI void moba_group(bf16_t* act, float* ml, int b, int hh, int j, int qpos, int slot, const bf16x8 (&qf)[4], bool live, bool isdiag, int ntiles, LAS const float* tab, LAS const unsigned char* lds, int lane) {
;     ...
;     const float bfar = tab[128];
;     const int kvb = j * 256;
;     LAS const unsigned char* Vb = lds + 32768;
;     f32x16 a0, a1, b0, b1;
;     moba_qk(a0, a1, bfar, lds, qf, r, h);
;     if (ntiles > 1) moba_qk(b0, b1, bfar, lds + 8192, qf, r, h);
.LBB0_493:
	ds_read_b32 v18, v190 offset:512
	ds_read_b128 v[2:5], v187
	ds_read_b128 v[252:255], v187 offset:512
	ds_read_b128 v[238:241], v187 offset:2048
	ds_read_b128 v[242:245], v187 offset:2560
	s_cmp_gt_i32 s33, 1
	s_cselect_b64 s[46:47], -1, 0
	s_cmp_lt_i32 s33, 2
	s_waitcnt lgkmcnt(4)
	v_mov_b32_e32 v19, v18
	v_mov_b32_e32 v20, v18
	v_mov_b32_e32 v21, v18
	v_mov_b32_e32 v22, v18
	v_mov_b32_e32 v23, v18
	v_mov_b32_e32 v24, v18
	v_mov_b32_e32 v25, v18
	v_mov_b32_e32 v26, v18
	v_mov_b32_e32 v27, v18
	v_mov_b32_e32 v28, v18
	v_mov_b32_e32 v29, v18
	v_mov_b32_e32 v30, v18
	v_mov_b32_e32 v31, v18
	v_mov_b32_e32 v32, v18
	v_mov_b32_e32 v33, v18
	s_nop 0
	s_waitcnt vmcnt(1) lgkmcnt(3)
	v_mfma_f32_32x32x16_bf16 v[36:51], v[2:5], v[118:121], v[18:33]
	ds_read_b128 v[2:5], v187 offset:4096
	s_waitcnt lgkmcnt(3)
	v_mfma_f32_32x32x16_bf16 v[102:117], v[252:255], v[118:121], v[18:33]
	ds_read_b128 v[252:255], v187 offset:4608
	s_waitcnt lgkmcnt(3)
	v_mfma_f32_32x32x16_bf16 v[36:51], v[238:241], v[126:129], v[36:51]
	ds_read_b128 v[238:241], v187 offset:6144
	s_waitcnt lgkmcnt(3)
	v_mfma_f32_32x32x16_bf16 v[102:117], v[242:245], v[126:129], v[102:117]
	ds_read_b128 v[242:245], v187 offset:6656
	s_waitcnt lgkmcnt(3)
	v_mfma_f32_32x32x16_bf16 v[36:51], v[2:5], v[130:133], v[36:51]
	s_waitcnt lgkmcnt(2)
	v_mfma_f32_32x32x16_bf16 v[102:117], v[252:255], v[130:133], v[102:117]
	s_waitcnt vmcnt(0) lgkmcnt(1)
	v_mfma_f32_32x32x16_bf16 v[36:51], v[238:241], v[122:125], v[36:51]
	s_waitcnt lgkmcnt(0)
	v_mfma_f32_32x32x16_bf16 v[102:117], v[242:245], v[122:125], v[102:117]
	s_cbranch_scc1 .LBB0_495
	ds_read_b128 v[2:5], v187 offset:8192
	ds_read_b128 v[252:255], v187 offset:8704
	ds_read_b128 v[238:241], v187 offset:10240
	ds_read_b128 v[242:245], v187 offset:10752
	v_mov_b64_e32 v[100:101], v[32:33]
	v_mov_b64_e32 v[98:99], v[30:31]
	v_mov_b64_e32 v[96:97], v[28:29]
	v_mov_b64_e32 v[94:95], v[26:27]
	v_mov_b64_e32 v[92:93], v[24:25]
	v_mov_b64_e32 v[90:91], v[22:23]
	v_mov_b64_e32 v[88:89], v[20:21]
	v_mov_b64_e32 v[86:87], v[18:19]
	s_waitcnt lgkmcnt(3)
	v_mfma_f32_32x32x16_bf16 v[68:83], v[2:5], v[118:121], v[18:33]
	ds_read_b128 v[2:5], v187 offset:12288
	s_waitcnt lgkmcnt(3)
	v_mfma_f32_32x32x16_bf16 v[86:101], v[252:255], v[118:121], v[86:101]
	ds_read_b128 v[252:255], v187 offset:12800
	s_waitcnt lgkmcnt(3)
	v_mfma_f32_32x32x16_bf16 v[68:83], v[238:241], v[126:129], v[68:83]
	ds_read_b128 v[238:241], v187 offset:14336
	s_waitcnt lgkmcnt(3)
	v_mfma_f32_32x32x16_bf16 v[86:101], v[242:245], v[126:129], v[86:101]
	ds_read_b128 v[242:245], v187 offset:14848
	s_waitcnt lgkmcnt(3)
	v_mfma_f32_32x32x16_bf16 v[68:83], v[2:5], v[130:133], v[68:83]
	s_waitcnt lgkmcnt(2)
	v_mfma_f32_32x32x16_bf16 v[86:101], v[252:255], v[130:133], v[86:101]
	s_waitcnt lgkmcnt(1)
	v_mfma_f32_32x32x16_bf16 v[68:83], v[238:241], v[122:125], v[68:83]
	s_waitcnt lgkmcnt(0)
	v_mfma_f32_32x32x16_bf16 v[86:101], v[242:245], v[122:125], v[86:101]
	v_subrev_u32_e32 v19, 63, v140
	v_sub_u32_e32 v0, v19, v144
	v_cmp_gt_i32_e32 vcc, s30, v0
	s_cbranch_vccnz .LBB0_496
	s_branch .LBB0_497

; DI float fast_exp2(float x) { return __builtin_amdgcn_exp2f(x); }
; DI void moba_softpv(f32x16& c0, f32x16& c1, f32x16& n0, f32x16& n1, bool has_next, bool first, int qpos, int kv0, float& m, float& l, f32x16& o0, f32x16& o1,
;                     float bfar, LAS const float* tab, LAS const unsigned char* Vt, int lane) {
;     ...
;     float ls = 0.f;
; #pragma unroll
;     for (int i = 0; i < 16; ++i) { c0[i] = fast_exp2(c0[i]); c1[i] = fast_exp2(c1[i]); ls += c0[i] + c1[i]; }
;     l += ls;
;     pv_tile(o0, o1, Vt, c0, c1, lane);
; DI void moba_group(bf16_t* act, float* ml, int b, int hh, int j, int qpos, int slot, const bf16x8 (&qf)[4], bool live, bool isdiag, int ntiles, LAS const float* tab, LAS const unsigned char* lds, int lane) {
;     ...
;         if (ntiles > 2) moba_qk(a0, a1, bfar - m, lds + 2 * 8192, qf, r, h);
;         moba_softpv(b0, b1, a0, a1, ntiles > 2, false, qpos, kvb + 64, m, l, o0, o1, bfar, tab, Vb + 8192, lane);
;         if (ntiles > 2) {
;             if (ntiles > 3) moba_qk(b0, b1, bfar - m, lds + 3 * 8192, qf, r, h);
;             moba_softpv(a0, a1, b0, b1, ntiles > 3, false, qpos, kvb + 128, m, l, o0, o1, bfar, tab, Vb + 2 * 8192, lane);
.LBB0_502:
	v_exp_f32_e32 v52, v36
	v_exp_f32_e32 v36, v102
	v_exp_f32_e32 v152, v37
	v_exp_f32_e32 v0, v103
	v_exp_f32_e32 v54, v38
	v_add_f32_e32 v153, v52, v36
	v_exp_f32_e32 v38, v104
	v_pk_add_f32 v[2:3], v[152:153], v[0:1]
	v_exp_f32_e32 v154, v39
	v_pk_add_f32 v[84:85], v[2:3], v[2:3] op_sel_hi:[0,1]
	v_exp_f32_e32 v84, v105
	v_add_f32_e32 v155, v54, v38
	v_exp_f32_e32 v56, v40
	v_exp_f32_e32 v40, v106
	v_pk_add_f32 v[2:3], v[154:155], v[84:85]
	v_exp_f32_e32 v156, v41
	v_pk_add_f32 v[102:103], v[2:3], v[2:3] op_sel_hi:[0,1]
	v_exp_f32_e32 v102, v107
	v_add_f32_e32 v157, v56, v40
	v_exp_f32_e32 v58, v42
	v_exp_f32_e32 v42, v108
	v_pk_add_f32 v[2:3], v[156:157], v[102:103]
	v_exp_f32_e32 v158, v43
	v_pk_add_f32 v[104:105], v[2:3], v[2:3] op_sel_hi:[0,1]
	v_exp_f32_e32 v104, v109
	v_add_f32_e32 v159, v58, v42
	v_exp_f32_e32 v60, v44
	v_exp_f32_e32 v44, v110
	v_pk_add_f32 v[2:3], v[158:159], v[104:105]
	v_exp_f32_e32 v160, v45
	v_pk_add_f32 v[106:107], v[2:3], v[2:3] op_sel_hi:[0,1]
	v_exp_f32_e32 v106, v111
	v_add_f32_e32 v161, v60, v44
	v_exp_f32_e32 v62, v46
	v_exp_f32_e32 v46, v112
	v_pk_add_f32 v[2:3], v[160:161], v[106:107]
	v_exp_f32_e32 v162, v47
	v_pk_add_f32 v[108:109], v[2:3], v[2:3] op_sel_hi:[0,1]
	v_exp_f32_e32 v108, v113
	v_add_f32_e32 v163, v62, v46
	v_exp_f32_e32 v64, v48
	v_exp_f32_e32 v48, v114
	v_pk_add_f32 v[2:3], v[162:163], v[108:109]
	v_exp_f32_e32 v164, v49
	v_pk_add_f32 v[110:111], v[2:3], v[2:3] op_sel_hi:[0,1]
	v_exp_f32_e32 v110, v115
	v_add_f32_e32 v165, v64, v48
	v_exp_f32_e32 v66, v50
	v_exp_f32_e32 v50, v116
	v_pk_add_f32 v[2:3], v[164:165], v[110:111]
	v_exp_f32_e32 v114, v51
	v_pk_add_f32 v[112:113], v[2:3], v[2:3] op_sel_hi:[0,1]
	v_exp_f32_e32 v112, v117
	ds_read_b64_tr_b16 v[6:7], v170 offset:32768
	ds_read_b64_tr_b16 v[8:9], v170 offset:33280
	ds_read_b64_tr_b16 v[10:11], v170 offset:36864
	ds_read_b64_tr_b16 v[12:13], v170 offset:37376
	v_add_f32_e32 v115, v66, v50
	v_cvt_pk_bf16_f32 v4, v56, v156
	v_pk_add_f32 v[2:3], v[114:115], v[112:113]
	v_cvt_pk_bf16_f32 v5, v58, v158
	v_add_f32_e32 v2, v2, v3
	v_add_f32_e32 v137, 0, v2
	v_cvt_pk_bf16_f32 v2, v52, v152
	v_cvt_pk_bf16_f32 v3, v54, v154
	ds_read_b64_tr_b16 v[218:219], v170 offset:33792
	ds_read_b64_tr_b16 v[220:221], v170 offset:34304
	ds_read_b64_tr_b16 v[222:223], v170 offset:37888
	ds_read_b64_tr_b16 v[224:225], v170 offset:38400
	s_waitcnt lgkmcnt(6)
	v_mfma_f32_32x32x16_bf16 v[20:35], v[6:9], v[2:5], 0
	v_cvt_pk_bf16_f32 v214, v60, v160
	v_cvt_pk_bf16_f32 v215, v62, v162
	v_cvt_pk_bf16_f32 v216, v64, v164
	v_cvt_pk_bf16_f32 v217, v66, v114
	s_and_b64 vcc, exec, s[46:47]
	s_waitcnt lgkmcnt(4)
	v_mfma_f32_32x32x16_bf16 v[2:17], v[10:13], v[2:5], 0
	s_waitcnt lgkmcnt(2)
	v_mfma_f32_32x32x16_bf16 v[20:35], v[218:221], v[214:217], v[20:35]
	s_waitcnt lgkmcnt(0)
	v_mfma_f32_32x32x16_bf16 v[2:17], v[222:225], v[214:217], v[2:17]
	ds_read_b64_tr_b16 v[218:219], v170 offset:34816
	ds_read_b64_tr_b16 v[220:221], v170 offset:35328
	ds_read_b64_tr_b16 v[222:223], v170 offset:38912
	ds_read_b64_tr_b16 v[224:225], v170 offset:39424
	v_cvt_pk_bf16_f32 v214, v36, v0
	v_cvt_pk_bf16_f32 v215, v38, v84
	v_cvt_pk_bf16_f32 v216, v40, v102
	v_cvt_pk_bf16_f32 v217, v42, v104
	s_waitcnt lgkmcnt(2)
	s_nop 0
	v_mfma_f32_32x32x16_bf16 v[20:35], v[218:221], v[214:217], v[20:35]
	s_waitcnt lgkmcnt(0)
	v_mfma_f32_32x32x16_bf16 v[2:17], v[222:225], v[214:217], v[2:17]
	ds_read_b64_tr_b16 v[218:219], v170 offset:35840
	ds_read_b64_tr_b16 v[220:221], v170 offset:36352
	ds_read_b64_tr_b16 v[222:223], v170 offset:39936
	ds_read_b64_tr_b16 v[224:225], v170 offset:40448
	v_cvt_pk_bf16_f32 v214, v44, v106
	v_cvt_pk_bf16_f32 v215, v46, v108
	v_cvt_pk_bf16_f32 v216, v48, v110
	v_cvt_pk_bf16_f32 v217, v50, v112
	s_waitcnt lgkmcnt(2)
	s_nop 0
	v_mfma_f32_32x32x16_bf16 v[20:35], v[218:221], v[214:217], v[20:35]
	s_waitcnt lgkmcnt(0)
	v_mfma_f32_32x32x16_bf16 v[2:17], v[222:225], v[214:217], v[2:17]
	s_cbranch_vccnz .LBB0_526
	s_cmp_lg_u32 s33, 2
	s_cselect_b64 s[46:47], -1, 0
	s_cmp_eq_u32 s33, 2
	s_cbranch_scc1 .LBB0_505
	ds_read_b128 v[102:105], v187 offset:16384
	ds_read_b128 v[252:255], v187 offset:16896
	ds_read_b128 v[238:241], v187 offset:18432
	ds_read_b128 v[242:245], v187 offset:18944
	v_sub_f32_e32 v36, v18, v150
	v_mov_b32_e32 v37, v36
	v_mov_b32_e32 v38, v36
	v_mov_b32_e32 v39, v36
	v_mov_b32_e32 v40, v36
	v_mov_b32_e32 v41, v36
	v_mov_b32_e32 v42, v36
	v_mov_b32_e32 v43, v36
	v_mov_b32_e32 v44, v36
	v_mov_b32_e32 v45, v36
	v_mov_b32_e32 v46, v36
	v_mov_b32_e32 v47, v36
	v_mov_b32_e32 v48, v36
	v_mov_b32_e32 v49, v36
	v_mov_b32_e32 v50, v36
	v_mov_b32_e32 v51, v36
	s_nop 0
	s_waitcnt lgkmcnt(3)
	v_mfma_f32_32x32x16_bf16 v[52:67], v[102:105], v[118:121], v[36:51]
	ds_read_b128 v[102:105], v187 offset:20480
	s_waitcnt lgkmcnt(3)
	v_mfma_f32_32x32x16_bf16 v[36:51], v[252:255], v[118:121], v[36:51]
	ds_read_b128 v[252:255], v187 offset:20992
	s_waitcnt lgkmcnt(3)
	v_mfma_f32_32x32x16_bf16 v[52:67], v[238:241], v[126:129], v[52:67]
	ds_read_b128 v[238:241], v187 offset:22528
	s_waitcnt lgkmcnt(3)
	v_mfma_f32_32x32x16_bf16 v[36:51], v[242:245], v[126:129], v[36:51]
	ds_read_b128 v[242:245], v187 offset:23040
	s_waitcnt lgkmcnt(3)
	v_mfma_f32_32x32x16_bf16 v[52:67], v[102:105], v[130:133], v[52:67]
	s_waitcnt lgkmcnt(2)
	v_mfma_f32_32x32x16_bf16 v[36:51], v[252:255], v[130:133], v[36:51]
	s_waitcnt lgkmcnt(1)
	v_mfma_f32_32x32x16_bf16 v[52:67], v[238:241], v[122:125], v[52:67]
	s_waitcnt lgkmcnt(0)
	v_mfma_f32_32x32x16_bf16 v[36:51], v[242:245], v[122:125], v[36:51]
	v_sub_u32_e32 v0, v19, v206
	v_cmp_gt_i32_e32 vcc, s30, v0
	s_cbranch_vccnz .LBB0_506
	s_branch .LBB0_507

; DI float fast_exp2(float x) { return __builtin_amdgcn_exp2f(x); }
; DI void moba_softpv(f32x16& c0, f32x16& c1, f32x16& n0, f32x16& n1, bool has_next, bool first, int qpos, int kv0, float& m, float& l, f32x16& o0, f32x16& o1,
;                     float bfar, LAS const float* tab, LAS const unsigned char* Vt, int lane) {
;     ...
;     float ls = 0.f;
; #pragma unroll
;     for (int i = 0; i < 16; ++i) { c0[i] = fast_exp2(c0[i]); c1[i] = fast_exp2(c1[i]); ls += c0[i] + c1[i]; }
;     l += ls;
;     pv_tile(o0, o1, Vt, c0, c1, lane);
; DI void moba_group(bf16_t* act, float* ml, int b, int hh, int j, int qpos, int slot, const bf16x8 (&qf)[4], bool live, bool isdiag, int ntiles, LAS const float* tab, LAS const unsigned char* lds, int lane) {
;     ...
;         moba_softpv(b0, b1, a0, a1, ntiles > 2, false, qpos, kvb + 64, m, l, o0, o1, bfar, tab, Vb + 8192, lane);
;         if (ntiles > 2) {
;             if (ntiles > 3) moba_qk(b0, b1, bfar - m, lds + 3 * 8192, qf, r, h);
.LBB0_511:
	v_exp_f32_e32 v84, v68
	v_exp_f32_e32 v68, v86
	v_exp_f32_e32 v0, v69
	v_exp_f32_e32 v102, v87
	v_exp_f32_e32 v104, v89
	v_add_f32_e32 v103, v68, v84
	v_exp_f32_e32 v108, v91
	v_pk_add_f32 v[86:87], v[102:103], v[0:1]
	v_exp_f32_e32 v112, v93
	v_pk_add_f32 v[106:107], v[86:87], v[86:87] op_sel_hi:[0,1]
	v_exp_f32_e32 v86, v70
	v_exp_f32_e32 v70, v88
	v_exp_f32_e32 v106, v71
	v_exp_f32_e32 v116, v95
	v_exp_f32_e32 v154, v97
	v_add_f32_e32 v105, v70, v86
	v_pk_add_f32 v[88:89], v[104:105], v[106:107]
	ds_read_b64_tr_b16 v[218:219], v170 offset:40960
	ds_read_b64_tr_b16 v[220:221], v170 offset:41472
	ds_read_b64_tr_b16 v[222:223], v170 offset:45056
	ds_read_b64_tr_b16 v[224:225], v170 offset:45568
	v_pk_add_f32 v[110:111], v[88:89], v[88:89] op_sel_hi:[0,1]
	v_exp_f32_e32 v88, v72
	v_exp_f32_e32 v72, v90
	v_exp_f32_e32 v110, v73
	v_exp_f32_e32 v158, v99
	v_cvt_pk_bf16_f32 v214, v84, v0
	v_add_f32_e32 v109, v72, v88
	v_pk_add_f32 v[90:91], v[108:109], v[110:111]
	v_cvt_pk_bf16_f32 v215, v86, v106
	v_pk_add_f32 v[114:115], v[90:91], v[90:91] op_sel_hi:[0,1]
	v_exp_f32_e32 v90, v74
	v_exp_f32_e32 v74, v92
	v_exp_f32_e32 v114, v75
	v_cvt_pk_bf16_f32 v216, v88, v110
	v_exp_f32_e32 v160, v101
	v_add_f32_e32 v113, v74, v90
	v_pk_add_f32 v[92:93], v[112:113], v[114:115]
	v_cvt_pk_bf16_f32 v217, v90, v114
	v_pk_add_f32 v[152:153], v[92:93], v[92:93] op_sel_hi:[0,1]
	v_exp_f32_e32 v92, v76
	v_exp_f32_e32 v76, v94
	v_exp_f32_e32 v152, v77
	s_waitcnt lgkmcnt(2)
	v_mfma_f32_32x32x16_bf16 v[20:35], v[218:221], v[214:217], v[20:35]
	s_and_b64 vcc, exec, s[46:47]
	v_add_f32_e32 v117, v76, v92
	v_add_f32_e64 v94, v116, v152
	v_add_f32_e64 v95, v117, v153
	v_add_f32_e64 v156, v94, v94
	v_add_f32_e64 v157, v94, v95
	v_exp_f32_e32 v94, v78
	v_exp_f32_e32 v78, v96
	v_exp_f32_e32 v156, v79
	s_waitcnt lgkmcnt(0)
	v_mfma_f32_32x32x16_bf16 v[2:17], v[222:225], v[214:217], v[2:17]
	ds_read_b64_tr_b16 v[218:219], v170 offset:41984
	ds_read_b64_tr_b16 v[220:221], v170 offset:42496
	ds_read_b64_tr_b16 v[222:223], v170 offset:46080
	ds_read_b64_tr_b16 v[224:225], v170 offset:46592
	v_add_f32_e32 v155, v78, v94
	v_pk_add_f32 v[96:97], v[154:155], v[156:157]
	v_cvt_pk_bf16_f32 v214, v92, v152
	v_pk_add_f32 v[162:163], v[96:97], v[96:97] op_sel_hi:[0,1]
	v_exp_f32_e32 v96, v80
	v_exp_f32_e32 v80, v98
	v_exp_f32_e32 v162, v81
	v_cvt_pk_bf16_f32 v215, v94, v156
	v_add_f32_e32 v159, v80, v96
	v_pk_add_f32 v[98:99], v[158:159], v[162:163]
	v_cvt_pk_bf16_f32 v216, v96, v162
	v_pk_add_f32 v[164:165], v[98:99], v[98:99] op_sel_hi:[0,1]
	v_exp_f32_e32 v98, v82
	v_exp_f32_e32 v164, v83
	v_exp_f32_e32 v82, v100
	v_cvt_pk_bf16_f32 v217, v98, v164
	s_waitcnt lgkmcnt(2)
	s_nop 0
	v_mfma_f32_32x32x16_bf16 v[20:35], v[218:221], v[214:217], v[20:35]
	v_add_f32_e32 v161, v82, v98
	v_add_f32_e64 v100, v160, v164
	v_add_f32_e64 v101, v161, v165
	v_add_f32_e32 v69, v100, v101
	v_add_f32_e32 v137, v137, v69
	s_waitcnt lgkmcnt(0)
	v_mfma_f32_32x32x16_bf16 v[2:17], v[222:225], v[214:217], v[2:17]
	ds_read_b64_tr_b16 v[218:219], v170 offset:43008
	ds_read_b64_tr_b16 v[220:221], v170 offset:43520
	ds_read_b64_tr_b16 v[222:223], v170 offset:47104
	ds_read_b64_tr_b16 v[224:225], v170 offset:47616
	v_cvt_pk_bf16_f32 v214, v68, v102
	v_cvt_pk_bf16_f32 v215, v70, v104
	v_cvt_pk_bf16_f32 v216, v72, v108
	v_cvt_pk_bf16_f32 v217, v74, v112
	s_waitcnt lgkmcnt(2)
	s_nop 0
	v_mfma_f32_32x32x16_bf16 v[20:35], v[218:221], v[214:217], v[20:35]
	s_waitcnt lgkmcnt(0)
	v_mfma_f32_32x32x16_bf16 v[2:17], v[222:225], v[214:217], v[2:17]
	ds_read_b64_tr_b16 v[218:219], v170 offset:44032
	ds_read_b64_tr_b16 v[220:221], v170 offset:44544
	ds_read_b64_tr_b16 v[222:223], v170 offset:48128
	ds_read_b64_tr_b16 v[224:225], v170 offset:48640
	v_cvt_pk_bf16_f32 v214, v76, v116
	v_cvt_pk_bf16_f32 v215, v78, v154
	v_cvt_pk_bf16_f32 v216, v80, v158
	v_cvt_pk_bf16_f32 v217, v82, v160
	s_waitcnt lgkmcnt(2)
	s_nop 0
	v_mfma_f32_32x32x16_bf16 v[20:35], v[218:221], v[214:217], v[20:35]
	s_waitcnt lgkmcnt(0)
	v_mfma_f32_32x32x16_bf16 v[2:17], v[222:225], v[214:217], v[2:17]
	s_cbranch_vccnz .LBB0_526
	s_cmp_gt_u32 s33, 3
	s_cselect_b64 s[46:47], -1, 0
	s_cmp_lt_u32 s33, 4
	s_cbranch_scc1 .LBB0_514
	ds_read_b128 v[100:103], v187 offset:24576
	ds_read_b128 v[252:255], v187 offset:25088
	ds_read_b128 v[238:241], v187 offset:26624
	ds_read_b128 v[242:245], v187 offset:27136
	v_sub_f32_e32 v68, v18, v150
	v_mov_b32_e32 v69, v68
	v_mov_b32_e32 v70, v68
	v_mov_b32_e32 v71, v68
	v_mov_b32_e32 v72, v68
	v_mov_b32_e32 v73, v68
	v_mov_b32_e32 v74, v68
	v_mov_b32_e32 v75, v68
	v_mov_b32_e32 v76, v68
	v_mov_b32_e32 v77, v68
	v_mov_b32_e32 v78, v68
	v_mov_b32_e32 v79, v68
	v_mov_b32_e32 v80, v68
	v_mov_b32_e32 v81, v68
	v_mov_b32_e32 v82, v68
	v_mov_b32_e32 v83, v68
	s_nop 0
	s_waitcnt lgkmcnt(3)
	v_mfma_f32_32x32x16_bf16 v[84:99], v[100:103], v[118:121], v[68:83]
	ds_read_b128 v[100:103], v187 offset:28672
	s_waitcnt lgkmcnt(3)
	v_mfma_f32_32x32x16_bf16 v[68:83], v[252:255], v[118:121], v[68:83]
	ds_read_b128 v[252:255], v187 offset:29184
	s_waitcnt lgkmcnt(3)
	v_mfma_f32_32x32x16_bf16 v[84:99], v[238:241], v[126:129], v[84:99]
	ds_read_b128 v[238:241], v187 offset:30720
	s_waitcnt lgkmcnt(3)
	v_mfma_f32_32x32x16_bf16 v[68:83], v[242:245], v[126:129], v[68:83]
	ds_read_b128 v[242:245], v187 offset:31232
	s_waitcnt lgkmcnt(3)
	v_mfma_f32_32x32x16_bf16 v[84:99], v[100:103], v[130:133], v[84:99]
	s_waitcnt lgkmcnt(2)
	v_mfma_f32_32x32x16_bf16 v[68:83], v[252:255], v[130:133], v[68:83]
	s_waitcnt lgkmcnt(1)
	v_mfma_f32_32x32x16_bf16 v[84:99], v[238:241], v[122:125], v[84:99]
	s_waitcnt lgkmcnt(0)
	v_mfma_f32_32x32x16_bf16 v[68:83], v[242:245], v[122:125], v[68:83]
	v_sub_u32_e32 v0, v19, v208
	v_cmp_gt_i32_e32 vcc, s30, v0
	s_cbranch_vccnz .LBB0_515
	s_branch .LBB0_516
